# grid barrier with one hop less: XCD leaders wait on the cross-XCD arrival counter (TOP >= target) instead of a release generation bumped by the last leader; applied to all 13 barrier instances
# speedup vs baseline: 1.0126x; 1.0060x over previous
.LBB0_91:
	s_or_b64 exec, exec, s[18:19]
	v_cvt_f32_u32_e32 v3, v0
	s_waitcnt vmcnt(0)
	v_readfirstlane_b32 s4, v2
	s_add_u32 s18, s8, 0x7500
	s_addc_u32 s19, s9, 0
	v_rcp_iflag_f32_e32 v3, v3
	v_add_u32_e32 v1, s4, v1
	v_add_u32_e32 v4, 1, v1
	s_mov_b64 s[20:21], 0
	v_mul_f32_e32 v2, 0x4f7ffffe, v3
	v_cvt_u32_f32_e32 v2, v2
	v_sub_u32_e32 v3, 0, v0
	v_mul_lo_u32 v3, v3, v2
	v_mul_hi_u32 v3, v2, v3
	v_add_u32_e32 v2, v2, v3
	v_mul_hi_u32 v2, v1, v2
	v_mul_lo_u32 v3, v2, v0
	v_sub_u32_e32 v1, v1, v3
	v_add_u32_e32 v5, 1, v2
	v_cmp_ge_u32_e32 vcc, v1, v0
	v_sub_u32_e32 v3, v1, v0
	s_nop 0
	v_cndmask_b32_e32 v2, v2, v5, vcc
	v_cndmask_b32_e32 v1, v1, v3, vcc
	v_add_u32_e32 v3, 1, v2
	v_cmp_ge_u32_e32 vcc, v1, v0
	s_nop 1
	v_cndmask_b32_e32 v2, v2, v3, vcc
	v_mul_lo_u32 v1, v0, v2
	v_add_u32_e32 v0, v1, v0
	v_cmp_ne_u32_e32 vcc, v4, v0
	v_mov_b32_e32 v2, v0
	v_mov_b64_e32 v[0:1], s[18:19]
	s_and_saveexec_b64 s[14:15], vcc
	s_cbranch_execz .LBB0_103
	v_mov_b32_e32 v0, 0
	global_load_dword v1, v0, s[18:19] offset:-256 sc1
	s_mov_b64 s[24:25], 0
	s_waitcnt vmcnt(0)
	v_cmp_lt_u32_e32 vcc, v1, v2
	s_and_saveexec_b64 s[22:23], vcc
	s_cbranch_execz .LBB0_102
	s_add_u32 s20, s8, 0x4200
	s_addc_u32 s21, s9, 0
	s_mov_b32 s4, 1
	s_mov_b64 s[8:9], 0
	s_branch .LBB0_95

.LBB0_97:
	global_load_dword v1, v0, s[18:19] offset:-256 sc1
	s_add_i32 s4, s4, 1
	s_mov_b64 s[26:27], -1
	s_waitcnt vmcnt(0)
	v_cmp_ge_u32_e32 vcc, v1, v2
	s_orn2_b64 s[30:31], vcc, exec
	s_branch .LBB0_94

.LBB0_246:
	s_or_b64 exec, exec, s[24:25]
	v_cvt_f32_u32_e32 v3, v0
	s_waitcnt vmcnt(0)
	v_readfirstlane_b32 s4, v2
	s_add_u32 s24, s8, 0x7500
	s_addc_u32 s25, s9, 0
	v_rcp_iflag_f32_e32 v3, v3
	v_add_u32_e32 v1, s4, v1
	v_add_u32_e32 v4, 1, v1
	s_mov_b64 s[26:27], 0
	v_mul_f32_e32 v2, 0x4f7ffffe, v3
	v_cvt_u32_f32_e32 v2, v2
	v_sub_u32_e32 v3, 0, v0
	v_mul_lo_u32 v3, v3, v2
	v_mul_hi_u32 v3, v2, v3
	v_add_u32_e32 v2, v2, v3
	v_mul_hi_u32 v2, v1, v2
	v_mul_lo_u32 v3, v2, v0
	v_sub_u32_e32 v1, v1, v3
	v_add_u32_e32 v5, 1, v2
	v_cmp_ge_u32_e32 vcc, v1, v0
	v_sub_u32_e32 v3, v1, v0
	s_nop 0
	v_cndmask_b32_e32 v2, v2, v5, vcc
	v_cndmask_b32_e32 v1, v1, v3, vcc
	v_add_u32_e32 v3, 1, v2
	v_cmp_ge_u32_e32 vcc, v1, v0
	s_nop 1
	v_cndmask_b32_e32 v2, v2, v3, vcc
	v_mul_lo_u32 v1, v0, v2
	v_add_u32_e32 v0, v1, v0
	v_cmp_ne_u32_e32 vcc, v4, v0
	v_mov_b32_e32 v2, v0
	v_mov_b64_e32 v[0:1], s[24:25]
	s_and_saveexec_b64 s[14:15], vcc
	s_cbranch_execz .LBB0_258
	v_mov_b32_e32 v0, 0
	global_load_dword v1, v0, s[24:25] offset:-256 sc1
	s_mov_b64 s[30:31], 0
	s_waitcnt vmcnt(0)
	v_cmp_lt_u32_e32 vcc, v1, v2
	s_and_saveexec_b64 s[28:29], vcc
	s_cbranch_execz .LBB0_257
	s_add_u32 s26, s8, 0x4200
	s_addc_u32 s27, s9, 0
	s_mov_b32 s4, 1
	s_mov_b64 s[8:9], 0
	s_branch .LBB0_250

.LBB0_252:
	global_load_dword v1, v0, s[24:25] offset:-256 sc1
	s_add_i32 s4, s4, 1
	s_mov_b64 s[34:35], -1
	s_waitcnt vmcnt(0)
	v_cmp_ge_u32_e32 vcc, v1, v2
	s_orn2_b64 s[38:39], vcc, exec
	s_branch .LBB0_249

.LBB0_358:
	s_or_b64 exec, exec, s[14:15]
	s_waitcnt vmcnt(0)
	v_readfirstlane_b32 s4, v3
	v_sub_u32_e32 v4, 0, v2
	s_add_u32 s12, s8, 0x7500
	v_add_u32_e32 v3, s4, v0
	v_cvt_f32_u32_e32 v0, v2
	s_addc_u32 s13, s9, 0
	s_mov_b64 s[24:25], 0
	v_rcp_iflag_f32_e32 v0, v0
	s_nop 0
	v_mul_f32_e32 v0, 0x4f7ffffe, v0
	v_cvt_u32_f32_e32 v0, v0
	v_mul_lo_u32 v4, v4, v0
	v_mul_hi_u32 v4, v0, v4
	v_add_u32_e32 v0, v0, v4
	v_mul_hi_u32 v0, v3, v0
	v_mul_lo_u32 v4, v0, v2
	v_sub_u32_e32 v4, v3, v4
	v_cmp_ge_u32_e32 vcc, v4, v2
	v_add_u32_e32 v5, 1, v0
	v_add_u32_e32 v3, 1, v3
	v_cndmask_b32_e32 v0, v0, v5, vcc
	v_sub_u32_e32 v5, v4, v2
	v_cndmask_b32_e32 v4, v4, v5, vcc
	v_cmp_ge_u32_e32 vcc, v4, v2
	v_add_u32_e32 v4, 1, v0
	s_nop 0
	v_cndmask_b32_e32 v0, v0, v4, vcc
	v_mul_lo_u32 v4, v2, v0
	v_add_u32_e32 v2, v4, v2
	v_cmp_ne_u32_e32 vcc, v3, v2
	v_mov_b32_e32 v0, v2
	v_mov_b64_e32 v[2:3], s[12:13]
	s_and_saveexec_b64 s[14:15], vcc
	s_cbranch_execz .LBB0_370
	global_load_dword v2, v1, s[12:13] offset:-256 sc1
	s_mov_b64 s[36:37], 0
	s_waitcnt vmcnt(0)
	v_cmp_lt_u32_e32 vcc, v2, v0
	s_and_saveexec_b64 s[26:27], vcc
	s_cbranch_execz .LBB0_369
	s_add_u32 s24, s8, 0x4200
	s_addc_u32 s25, s9, 0
	s_mov_b32 s4, 1
	s_mov_b64 s[8:9], 0
	s_branch .LBB0_362

.LBB0_364:
	global_load_dword v2, v1, s[12:13] offset:-256 sc1
	s_add_i32 s4, s4, 1
	s_mov_b64 s[42:43], -1
	s_waitcnt vmcnt(0)
	v_cmp_ge_u32_e32 vcc, v2, v0
	s_orn2_b64 s[40:41], vcc, exec
	s_branch .LBB0_361

.Lko_g1423:
	s_or_b64 exec, exec, s[26:27]
	s_waitcnt vmcnt(0)
	v_readfirstlane_b32 s4, v3
	v_sub_u32_e32 v4, 0, v2
	s_add_u32 s24, s10, 0x7500
	v_add_u32_e32 v3, s4, v0
	v_cvt_f32_u32_e32 v0, v2
	s_addc_u32 s25, s11, 0
	s_mov_b64 s[28:29], 0
	v_rcp_iflag_f32_e32 v0, v0
	s_nop 0
	v_mul_f32_e32 v0, 0x4f7ffffe, v0
	v_cvt_u32_f32_e32 v0, v0
	v_mul_lo_u32 v4, v4, v0
	v_mul_hi_u32 v4, v0, v4
	v_add_u32_e32 v0, v0, v4
	v_mul_hi_u32 v0, v3, v0
	v_mul_lo_u32 v4, v0, v2
	v_sub_u32_e32 v4, v3, v4
	v_cmp_ge_u32_e32 vcc, v4, v2
	v_add_u32_e32 v5, 1, v0
	v_add_u32_e32 v3, 1, v3
	v_cndmask_b32_e32 v0, v0, v5, vcc
	v_sub_u32_e32 v5, v4, v2
	v_cndmask_b32_e32 v4, v4, v5, vcc
	v_cmp_ge_u32_e32 vcc, v4, v2
	v_add_u32_e32 v4, 1, v0
	s_nop 0
	v_cndmask_b32_e32 v0, v0, v4, vcc
	v_mul_lo_u32 v4, v2, v0
	v_add_u32_e32 v2, v4, v2
	v_cmp_ne_u32_e32 vcc, v3, v2
	v_mov_b32_e32 v0, v2
	v_mov_b64_e32 v[2:3], s[24:25]
	s_and_saveexec_b64 s[26:27], vcc
	s_cbranch_execz .Lko_g1435
	global_load_dword v2, v1, s[24:25] offset:-256 sc1
	s_mov_b64 s[40:41], 0
	s_waitcnt vmcnt(0)
	v_cmp_lt_u32_e32 vcc, v2, v0
	s_and_saveexec_b64 s[36:37], vcc
	s_cbranch_execz .Lko_g1434
	s_add_u32 s28, s10, 0x4200
	s_addc_u32 s29, s11, 0
	s_mov_b32 s4, 1
	s_mov_b64 s[10:11], 0
	s_branch .Lko_g1427

.Lko_g1429:
	global_load_dword v2, v1, s[24:25] offset:-256 sc1
	s_add_i32 s4, s4, 1
	s_mov_b64 s[44:45], -1
	s_waitcnt vmcnt(0)
	v_cmp_ge_u32_e32 vcc, v2, v0
	s_orn2_b64 s[42:43], vcc, exec
	s_branch .Lko_g1426

.LBB0_1645:
	s_or_b64 exec, exec, s[24:25]
	s_waitcnt vmcnt(0)
	v_readfirstlane_b32 s4, v3
	v_sub_u32_e32 v4, 0, v2
	s_add_u32 s12, s8, 0x7500
	v_add_u32_e32 v3, s4, v0
	v_cvt_f32_u32_e32 v0, v2
	s_addc_u32 s13, s9, 0
	s_mov_b64 s[26:27], 0
	v_rcp_iflag_f32_e32 v0, v0
	s_nop 0
	v_mul_f32_e32 v0, 0x4f7ffffe, v0
	v_cvt_u32_f32_e32 v0, v0
	v_mul_lo_u32 v4, v4, v0
	v_mul_hi_u32 v4, v0, v4
	v_add_u32_e32 v0, v0, v4
	v_mul_hi_u32 v0, v3, v0
	v_mul_lo_u32 v4, v0, v2
	v_sub_u32_e32 v4, v3, v4
	v_cmp_ge_u32_e32 vcc, v4, v2
	v_add_u32_e32 v5, 1, v0
	v_add_u32_e32 v3, 1, v3
	v_cndmask_b32_e32 v0, v0, v5, vcc
	v_sub_u32_e32 v5, v4, v2
	v_cndmask_b32_e32 v4, v4, v5, vcc
	v_cmp_ge_u32_e32 vcc, v4, v2
	v_add_u32_e32 v4, 1, v0
	s_nop 0
	v_cndmask_b32_e32 v0, v0, v4, vcc
	v_mul_lo_u32 v4, v2, v0
	v_add_u32_e32 v2, v4, v2
	v_cmp_ne_u32_e32 vcc, v3, v2
	v_mov_b32_e32 v0, v2
	v_mov_b64_e32 v[2:3], s[12:13]
	s_and_saveexec_b64 s[24:25], vcc
	s_cbranch_execz .LBB0_1657
	global_load_dword v2, v1, s[12:13] offset:-256 sc1
	s_mov_b64 s[36:37], 0
	s_waitcnt vmcnt(0)
	v_cmp_lt_u32_e32 vcc, v2, v0
	s_and_saveexec_b64 s[28:29], vcc
	s_cbranch_execz .LBB0_1656
	s_add_u32 s26, s8, 0x4200
	s_addc_u32 s27, s9, 0
	s_mov_b32 s4, 1
	s_mov_b64 s[8:9], 0
	s_branch .LBB0_1649
